# EpiRelu2: the 12 remaining redundant canonicalising v_max replaced by s_nop 0 (same wait states, no VALU work)
# speedup vs baseline: 1.0071x; 1.0010x over previous
; __device__ __forceinline__ unsigned cvt_pk_bf16(float lo, float hi) { unsigned r; asm volatile("v_cvt_pk_bf16_f32 %0, %1, %2" : "=v"(r) : "v"(lo), "v"(hi)); return r; }
; __device__ __forceinline__ float rs_of(const float* ss, int row) { return 1.0f / sqrtf(ss[row] * (1.0f / 2048.0f) + 1e-5f); }
; __device__ __forceinline__ u32x4 pack8(f32x4 a, f32x4 b) { u32x4 w; w.x = cvt_pk_bf16(a[0], a[1]); w.y = cvt_pk_bf16(a[2], a[3]); w.z = cvt_pk_bf16(b[0], b[1]); w.w = cvt_pk_bf16(b[2], b[3]); return w; }
; __device__ __forceinline__ void line_xchg(u32x4& v0, u32x4& v1, bool hb) {
;     u32x4 send = hb ? v0 : v1, recv;
;     recv.x = (unsigned)__builtin_amdgcn_mov_dpp((int)send.x, 0x128, 0xF, 0xF, false); recv.y = (unsigned)__builtin_amdgcn_mov_dpp((int)send.y, 0x128, 0xF, 0xF, false);
;     recv.z = (unsigned)__builtin_amdgcn_mov_dpp((int)send.z, 0x128, 0xF, 0xF, false); recv.w = (unsigned)__builtin_amdgcn_mov_dpp((int)send.w, 0x128, 0xF, 0xF, false);
;     const u32x4 o0 = hb ? recv : v0, o1 = hb ? v1 : recv; v0 = o0; v1 = o1;
; }
;     __device__ __forceinline__ void operator()(const f32x4 (&acc)[2][2][4][2], const Unit& u, int wr, int wc, int fr, int fq) const {
;     ...
; #pragma unroll
;         for (int ai = 0; ai < 2; ++ai)
; #pragma unroll
;             for (int m = 0; m < 4; ++m) {
;                 const int row = row0 + ai * HALF + m * 16; const float rr = ss ? rs_of(ss, row) : 1.0f;
;                 u32x4 v[2];
; #pragma unroll
;                 for (int bj = 0; bj < 2; ++bj) {
;                     f32x4 a = __builtin_elementwise_max(acc[ai][bj][m][0], z) * rr, b = __builtin_elementwise_max(acc[ai][bj][m][1], z) * rr;
;                     v[bj] = pack8(a * a, b * b);
;                 }
;                 line_xchg(v[0], v[1], hb);
;                 bf16_t* p = O + (size_t)(srow0 + ai * HALF + m * 16) * ldc + scol;
;                 __builtin_nontemporal_store(v[0], (u32x4*)p); __builtin_nontemporal_store(v[1], (u32x4*)(p + (size_t)8 * ldc));
;             }
.Lrr_hit:
	v_max_f32_e32 v127, 0, v127
	v_max_f32_e32 v126, 0, v126
	v_max_f32_e32 v125, 0, v125
	v_max_f32_e32 v124, 0, v124
	v_max_f32_e32 v123, 0, v123
	v_max_f32_e32 v122, 0, v122
	v_max_f32_e32 v121, 0, v121
	v_max_f32_e32 v120, 0, v120
	v_max_f32_e32 v115, 0, v115
	v_max_f32_e32 v114, 0, v114
	v_max_f32_e32 v113, 0, v113
	v_max_f32_e32 v112, 0, v112
	v_max_f32_e32 v119, 0, v119
	v_max_f32_e32 v118, 0, v118
	v_max_f32_e32 v117, 0, v117
	v_max_f32_e32 v116, 0, v116
	v_ashrrev_i32_e32 v139, 31, v138
	v_max_f32_e32 v111, 0, v111
	v_max_f32_e32 v110, 0, v110
	v_max_f32_e32 v109, 0, v109
	v_max_f32_e32 v108, 0, v108
	v_max_f32_e32 v107, 0, v107
	v_max_f32_e32 v106, 0, v106
	v_max_f32_e32 v105, 0, v105
	v_max_f32_e32 v104, 0, v104
	v_max_f32_e32 v97, 0, v97
	v_max_f32_e32 v96, 0, v96
	v_max_f32_e32 v103, 0, v103
	v_max_f32_e32 v102, 0, v102
	v_max_f32_e32 v101, 0, v101
	v_max_f32_e32 v100, 0, v100
	v_max_f32_e32 v99, 0, v99
	v_max_f32_e32 v98, 0, v98
	v_max_f32_e32 v95, 0, v95
	v_max_f32_e32 v94, 0, v94
	v_max_f32_e32 v93, 0, v93
	v_max_f32_e32 v92, 0, v92
	v_max_f32_e32 v91, 0, v91
	v_max_f32_e32 v90, 0, v90
	v_max_f32_e32 v89, 0, v89
	v_max_f32_e32 v88, 0, v88
	s_nop 0
	s_nop 0
	s_nop 0
	s_nop 0
	s_nop 0
	s_nop 0
	v_mov_b32_e32 v140, v234
	v_pk_mul_f32 v[124:125], v[124:125], v[140:141] op_sel_hi:[1,0]
	v_pk_mul_f32 v[126:127], v[126:127], v[140:141] op_sel_hi:[1,0]
	v_pk_mul_f32 v[120:121], v[120:121], v[140:141] op_sel_hi:[1,0]
	v_pk_mul_f32 v[122:123], v[122:123], v[140:141] op_sel_hi:[1,0]
	v_pk_mul_f32 v[112:113], v[112:113], v[140:141] op_sel_hi:[1,0]
	v_pk_mul_f32 v[114:115], v[114:115], v[140:141] op_sel_hi:[1,0]
	v_pk_mul_f32 v[126:127], v[126:127], v[126:127]
	v_pk_mul_f32 v[124:125], v[124:125], v[124:125]
	v_pk_mul_f32 v[122:123], v[122:123], v[122:123]
	v_pk_mul_f32 v[120:121], v[120:121], v[120:121]
	v_pk_mul_f32 v[116:117], v[116:117], v[140:141] op_sel_hi:[1,0]
	v_pk_mul_f32 v[118:119], v[118:119], v[140:141] op_sel_hi:[1,0]
	v_pk_mul_f32 v[114:115], v[114:115], v[114:115]
	v_pk_mul_f32 v[112:113], v[112:113], v[112:113]
	v_cvt_pk_bf16_f32 v124, v124, v125
	v_cvt_pk_bf16_f32 v125, v126, v127
	v_cvt_pk_bf16_f32 v120, v120, v121
	v_cvt_pk_bf16_f32 v121, v122, v123
	v_pk_mul_f32 v[118:119], v[118:119], v[118:119]
	v_pk_mul_f32 v[116:117], v[116:117], v[116:117]
	v_max_f32_e32 v81, 0, v81
	v_cvt_pk_bf16_f32 v122, v116, v117
	v_cvt_pk_bf16_f32 v123, v118, v119
	v_cvt_pk_bf16_f32 v126, v112, v113
	v_cvt_pk_bf16_f32 v115, v114, v115
	v_max_f32_e32 v80, 0, v80
	v_cndmask_b32_e64 v113, v126, v120, s[2:3]
	v_cndmask_b32_e64 v114, v123, v125, s[2:3]
	v_cndmask_b32_e64 v112, v115, v121, s[2:3]
	v_mov_b32_dpp v137, v113 row_ror:8 row_mask:0xf bank_mask:0xf
	v_mov_b32_dpp v114, v114 row_ror:8 row_mask:0xf bank_mask:0xf
	v_cndmask_b32_e64 v116, v122, v124, s[2:3]
	v_mov_b32_dpp v140, v112 row_ror:8 row_mask:0xf bank_mask:0xf
	v_cndmask_b32_e64 v117, v125, v114, s[2:3]
	v_cndmask_b32_e64 v118, v120, v137, s[2:3]
	v_cndmask_b32_e64 v113, v114, v123, s[2:3]
	v_cndmask_b32_e64 v114, v137, v126, s[2:3]
	v_ashrrev_i32_e32 v137, 31, v136
	v_mov_b32_dpp v127, v116 row_ror:8 row_mask:0xf bank_mask:0xf
	v_cndmask_b32_e64 v119, v121, v140, s[2:3]
	v_lshlrev_b64 v[120:121], 14, v[136:137]
	v_cndmask_b32_e64 v112, v127, v122, s[2:3]
	v_lshl_add_u64 v[120:121], s[10:11], 0, v[120:121]
	v_lshlrev_b64 v[122:123], 1, v[138:139]
	v_cndmask_b32_e64 v116, v124, v127, s[2:3]
	v_lshl_add_u64 v[120:121], v[120:121], 0, v[122:123]
	global_store_dwordx4 v[120:121], v[116:119], off nt
	v_cndmask_b32_e64 v115, v140, v115, s[2:3]
	v_max_f32_e32 v87, 0, v87
	v_add_co_u32_e32 v116, vcc, s79, v120
	v_max_f32_e32 v86, 0, v86
	s_nop 0
	v_addc_co_u32_e32 v117, vcc, 0, v121, vcc
	global_store_dwordx4 v[116:117], v[112:115], off nt
	v_max_f32_e32 v85, 0, v85
	v_max_f32_e32 v84, 0, v84
	v_max_f32_e32 v83, 0, v83
	v_max_f32_e32 v82, 0, v82
	s_nop 0
	v_max_f32_e32 v79, 0, v79
	v_max_f32_e32 v78, 0, v78
	v_max_f32_e32 v77, 0, v77
	v_max_f32_e32 v76, 0, v76
	v_max_f32_e32 v75, 0, v75
	v_max_f32_e32 v74, 0, v74
	v_max_f32_e32 v73, 0, v73
	v_max_f32_e32 v72, 0, v72
	v_max_f32_e32 v65, 0, v65
	v_max_f32_e32 v64, 0, v64
	v_max_f32_e32 v71, 0, v71
	v_max_f32_e32 v70, 0, v70
	v_max_f32_e32 v69, 0, v69
	v_max_f32_e32 v68, 0, v68
	v_max_f32_e32 v67, 0, v67
	v_max_f32_e32 v66, 0, v66
	v_max_f32_e32 v63, 0, v63
	v_max_f32_e32 v62, 0, v62
	v_max_f32_e32 v61, 0, v61
	v_max_f32_e32 v60, 0, v60
	v_max_f32_e32 v59, 0, v59
	v_max_f32_e32 v58, 0, v58
	v_max_f32_e32 v57, 0, v57
	v_max_f32_e32 v56, 0, v56
	v_max_f32_e32 v49, 0, v49
	v_max_f32_e32 v48, 0, v48
	v_max_f32_e32 v55, 0, v55
	v_max_f32_e32 v54, 0, v54
	v_max_f32_e32 v53, 0, v53
	v_max_f32_e32 v52, 0, v52
	v_max_f32_e32 v51, 0, v51
	v_max_f32_e32 v50, 0, v50
	s_nop 0
	v_max_f32_e32 v45, 0, v45
	v_max_f32_e32 v44, 0, v44
	s_nop 0
	s_nop 0
	v_max_f32_e32 v41, 0, v41
	v_max_f32_e32 v40, 0, v40
	v_max_f32_e32 v39, 0, v39
	v_max_f32_e32 v38, 0, v38
	v_max_f32_e32 v37, 0, v37
	v_max_f32_e32 v36, 0, v36
	s_nop 0
	v_mov_b32_e32 v112, v235
	v_pk_mul_f32 v[108:109], v[108:109], v[112:113] op_sel_hi:[1,0]
	v_pk_mul_f32 v[110:111], v[110:111], v[112:113] op_sel_hi:[1,0]
	v_pk_mul_f32 v[104:105], v[104:105], v[112:113] op_sel_hi:[1,0]
	v_pk_mul_f32 v[106:107], v[106:107], v[112:113] op_sel_hi:[1,0]
	v_pk_mul_f32 v[96:97], v[96:97], v[112:113] op_sel_hi:[1,0]
	v_pk_mul_f32 v[110:111], v[110:111], v[110:111]
	v_pk_mul_f32 v[108:109], v[108:109], v[108:109]
	v_pk_mul_f32 v[106:107], v[106:107], v[106:107]
	v_pk_mul_f32 v[104:105], v[104:105], v[104:105]
	v_pk_mul_f32 v[100:101], v[100:101], v[112:113] op_sel_hi:[1,0]
; __device__ __forceinline__ unsigned cvt_pk_bf16(float lo, float hi) { unsigned r; asm volatile("v_cvt_pk_bf16_f32 %0, %1, %2" : "=v"(r) : "v"(lo), "v"(hi)); return r; }
; __device__ __forceinline__ float rs_of(const float* ss, int row) { return 1.0f / sqrtf(ss[row] * (1.0f / 2048.0f) + 1e-5f); }
; __device__ __forceinline__ u32x4 pack8(f32x4 a, f32x4 b) { u32x4 w; w.x = cvt_pk_bf16(a[0], a[1]); w.y = cvt_pk_bf16(a[2], a[3]); w.z = cvt_pk_bf16(b[0], b[1]); w.w = cvt_pk_bf16(b[2], b[3]); return w; }
; __device__ __forceinline__ void line_xchg(u32x4& v0, u32x4& v1, bool hb) {
;     u32x4 send = hb ? v0 : v1, recv;
;     recv.x = (unsigned)__builtin_amdgcn_mov_dpp((int)send.x, 0x128, 0xF, 0xF, false); recv.y = (unsigned)__builtin_amdgcn_mov_dpp((int)send.y, 0x128, 0xF, 0xF, false);
;     recv.z = (unsigned)__builtin_amdgcn_mov_dpp((int)send.z, 0x128, 0xF, 0xF, false); recv.w = (unsigned)__builtin_amdgcn_mov_dpp((int)send.w, 0x128, 0xF, 0xF, false);
;     const u32x4 o0 = hb ? recv : v0, o1 = hb ? v1 : recv; v0 = o0; v1 = o1;
; }
;     __device__ __forceinline__ void operator()(const f32x4 (&acc)[2][2][4][2], const Unit& u, int wr, int wc, int fr, int fq) const {
;     ...
; #pragma unroll
;         for (int ai = 0; ai < 2; ++ai)
; #pragma unroll
;             for (int m = 0; m < 4; ++m) {
;                 const int row = row0 + ai * HALF + m * 16; const float rr = ss ? rs_of(ss, row) : 1.0f;
;                 u32x4 v[2];
; #pragma unroll
;                 for (int bj = 0; bj < 2; ++bj) {
;                     f32x4 a = __builtin_elementwise_max(acc[ai][bj][m][0], z) * rr, b = __builtin_elementwise_max(acc[ai][bj][m][1], z) * rr;
;                     v[bj] = pack8(a * a, b * b);
;                 }
;                 line_xchg(v[0], v[1], hb);
;                 bf16_t* p = O + (size_t)(srow0 + ai * HALF + m * 16) * ldc + scol;
;                 __builtin_nontemporal_store(v[0], (u32x4*)p); __builtin_nontemporal_store(v[1], (u32x4*)(p + (size_t)8 * ldc));
;             }
	v_pk_mul_f32 v[102:103], v[102:103], v[112:113] op_sel_hi:[1,0]
	v_pk_mul_f32 v[98:99], v[98:99], v[112:113] op_sel_hi:[1,0]
	v_pk_mul_f32 v[96:97], v[96:97], v[96:97]
	v_cvt_pk_bf16_f32 v108, v108, v109
	v_cvt_pk_bf16_f32 v109, v110, v111
	v_cvt_pk_bf16_f32 v104, v104, v105
	v_cvt_pk_bf16_f32 v105, v106, v107
	v_pk_mul_f32 v[102:103], v[102:103], v[102:103]
	v_pk_mul_f32 v[100:101], v[100:101], v[100:101]
	v_pk_mul_f32 v[98:99], v[98:99], v[98:99]
	v_cvt_pk_bf16_f32 v106, v100, v101
	v_cvt_pk_bf16_f32 v107, v102, v103
	v_cvt_pk_bf16_f32 v110, v96, v97
	s_nop 0
	v_cndmask_b32_e64 v97, v110, v104, s[2:3]
	v_cvt_pk_bf16_f32 v99, v98, v99
	v_cndmask_b32_e64 v98, v107, v109, s[2:3]
	v_cndmask_b32_e64 v96, v99, v105, s[2:3]
	v_mov_b32_dpp v112, v97 row_ror:8 row_mask:0xf bank_mask:0xf
	v_cndmask_b32_e64 v102, v104, v112, s[2:3]
	v_mov_b32_dpp v113, v96 row_ror:8 row_mask:0xf bank_mask:0xf
	v_or_b32_e32 v104, 16, v136
	v_cndmask_b32_e64 v103, v105, v113, s[2:3]
	v_ashrrev_i32_e32 v105, 31, v104
	v_cndmask_b32_e64 v100, v106, v108, s[2:3]
	v_lshlrev_b64 v[104:105], 14, v[104:105]
	v_mov_b32_dpp v98, v98 row_ror:8 row_mask:0xf bank_mask:0xf
	v_mov_b32_dpp v111, v100 row_ror:8 row_mask:0xf bank_mask:0xf
	v_lshl_add_u64 v[104:105], s[10:11], 0, v[104:105]
	v_cndmask_b32_e64 v100, v108, v111, s[2:3]
	v_cndmask_b32_e64 v101, v109, v98, s[2:3]
	v_lshl_add_u64 v[104:105], v[104:105], 0, v[122:123]
	global_store_dwordx4 v[104:105], v[100:103], off nt
	v_cndmask_b32_e64 v96, v111, v106, s[2:3]
	v_cndmask_b32_e64 v97, v98, v107, s[2:3]
	v_add_co_u32_e32 v100, vcc, s79, v104
	v_cndmask_b32_e64 v98, v112, v110, s[2:3]
	v_cndmask_b32_e64 v99, v113, v99, s[2:3]
	v_addc_co_u32_e32 v101, vcc, 0, v105, vcc
	global_store_dwordx4 v[100:101], v[96:99], off nt
	v_max_f32_e32 v33, 0, v33
	v_max_f32_e32 v32, 0, v32
	v_max_f32_e32 v47, 0, v47
	v_max_f32_e32 v46, 0, v46
	v_max_f32_e32 v43, 0, v43
	v_max_f32_e32 v42, 0, v42
	v_max_f32_e32 v35, 0, v35
	v_max_f32_e32 v34, 0, v34
	v_max_f32_e32 v29, 0, v29
	v_max_f32_e32 v28, 0, v28
	v_max_f32_e32 v25, 0, v25
	v_max_f32_e32 v24, 0, v24
	v_max_f32_e32 v23, 0, v23
	v_max_f32_e32 v22, 0, v22
	v_max_f32_e32 v21, 0, v21
	v_max_f32_e32 v20, 0, v20
	v_max_f32_e32 v17, 0, v17
	v_max_f32_e32 v16, 0, v16
	v_max_f32_e32 v31, 0, v31
	v_max_f32_e32 v30, 0, v30
	v_max_f32_e32 v27, 0, v27
	v_max_f32_e32 v26, 0, v26
	v_max_f32_e32 v19, 0, v19
	v_max_f32_e32 v18, 0, v18
	v_max_f32_e32 v15, 0, v15
	v_max_f32_e32 v14, 0, v14
	v_max_f32_e32 v13, 0, v13
	v_max_f32_e32 v12, 0, v12
	v_max_f32_e32 v11, 0, v11
	v_max_f32_e32 v10, 0, v10
	v_max_f32_e32 v9, 0, v9
	v_max_f32_e32 v8, 0, v8
	v_max_f32_e32 v1, 0, v1
	v_max_f32_e32 v0, 0, v0
	v_max_f32_e32 v7, 0, v7
	v_max_f32_e32 v6, 0, v6
	v_max_f32_e32 v5, 0, v5
	v_max_f32_e32 v4, 0, v4
	v_max_f32_e32 v3, 0, v3
	v_max_f32_e32 v2, 0, v2
	v_mov_b32_e32 v96, v236
	v_pk_mul_f32 v[92:93], v[92:93], v[96:97] op_sel_hi:[1,0]
	v_pk_mul_f32 v[94:95], v[94:95], v[96:97] op_sel_hi:[1,0]
	v_pk_mul_f32 v[88:89], v[88:89], v[96:97] op_sel_hi:[1,0]
	v_pk_mul_f32 v[90:91], v[90:91], v[96:97] op_sel_hi:[1,0]
	v_pk_mul_f32 v[80:81], v[80:81], v[96:97] op_sel_hi:[1,0]
	v_pk_mul_f32 v[94:95], v[94:95], v[94:95]
	v_pk_mul_f32 v[92:93], v[92:93], v[92:93]
	v_pk_mul_f32 v[90:91], v[90:91], v[90:91]
	v_pk_mul_f32 v[88:89], v[88:89], v[88:89]
	v_pk_mul_f32 v[84:85], v[84:85], v[96:97] op_sel_hi:[1,0]
	v_pk_mul_f32 v[86:87], v[86:87], v[96:97] op_sel_hi:[1,0]
	v_pk_mul_f32 v[82:83], v[82:83], v[96:97] op_sel_hi:[1,0]
	v_pk_mul_f32 v[80:81], v[80:81], v[80:81]
	v_cvt_pk_bf16_f32 v92, v92, v93
	v_cvt_pk_bf16_f32 v93, v94, v95
	v_cvt_pk_bf16_f32 v88, v88, v89
	v_cvt_pk_bf16_f32 v89, v90, v91
	v_pk_mul_f32 v[86:87], v[86:87], v[86:87]
	v_pk_mul_f32 v[84:85], v[84:85], v[84:85]
	v_pk_mul_f32 v[82:83], v[82:83], v[82:83]
	v_cvt_pk_bf16_f32 v90, v84, v85
	v_cvt_pk_bf16_f32 v91, v86, v87
	v_cvt_pk_bf16_f32 v94, v80, v81
	s_nop 0
	v_cndmask_b32_e64 v81, v94, v88, s[2:3]
	v_cvt_pk_bf16_f32 v83, v82, v83
	v_cndmask_b32_e64 v82, v91, v93, s[2:3]
	v_cndmask_b32_e64 v80, v83, v89, s[2:3]
	v_mov_b32_dpp v96, v81 row_ror:8 row_mask:0xf bank_mask:0xf
	v_cndmask_b32_e64 v86, v88, v96, s[2:3]
	v_mov_b32_dpp v97, v80 row_ror:8 row_mask:0xf bank_mask:0xf
	v_or_b32_e32 v88, 32, v136
	v_cndmask_b32_e64 v87, v89, v97, s[2:3]
	v_ashrrev_i32_e32 v89, 31, v88
	v_cndmask_b32_e64 v84, v90, v92, s[2:3]
	v_lshlrev_b64 v[88:89], 14, v[88:89]
	v_mov_b32_dpp v82, v82 row_ror:8 row_mask:0xf bank_mask:0xf
	v_mov_b32_dpp v95, v84 row_ror:8 row_mask:0xf bank_mask:0xf
	v_lshl_add_u64 v[88:89], s[10:11], 0, v[88:89]
	v_cndmask_b32_e64 v84, v92, v95, s[2:3]
	v_cndmask_b32_e64 v85, v93, v82, s[2:3]
	v_lshl_add_u64 v[88:89], v[88:89], 0, v[122:123]
	global_store_dwordx4 v[88:89], v[84:87], off nt
	v_cndmask_b32_e64 v80, v95, v90, s[2:3]
	v_cndmask_b32_e64 v81, v82, v91, s[2:3]
	v_add_co_u32_e32 v84, vcc, s79, v88
	v_cndmask_b32_e64 v82, v96, v94, s[2:3]
	v_cndmask_b32_e64 v83, v97, v83, s[2:3]
	v_addc_co_u32_e32 v85, vcc, 0, v89, vcc
	global_store_dwordx4 v[84:85], v[80:83], off nt
	s_nop 1
	v_mov_b32_e32 v80, v237
	v_pk_mul_f32 v[76:77], v[76:77], v[80:81] op_sel_hi:[1,0]
	v_pk_mul_f32 v[78:79], v[78:79], v[80:81] op_sel_hi:[1,0]
	v_pk_mul_f32 v[72:73], v[72:73], v[80:81] op_sel_hi:[1,0]
	v_pk_mul_f32 v[74:75], v[74:75], v[80:81] op_sel_hi:[1,0]
	v_pk_mul_f32 v[64:65], v[64:65], v[80:81] op_sel_hi:[1,0]
	v_pk_mul_f32 v[78:79], v[78:79], v[78:79]
	v_pk_mul_f32 v[76:77], v[76:77], v[76:77]
	v_pk_mul_f32 v[74:75], v[74:75], v[74:75]
	v_pk_mul_f32 v[72:73], v[72:73], v[72:73]
	v_pk_mul_f32 v[68:69], v[68:69], v[80:81] op_sel_hi:[1,0]
	v_pk_mul_f32 v[70:71], v[70:71], v[80:81] op_sel_hi:[1,0]
; __device__ __forceinline__ unsigned cvt_pk_bf16(float lo, float hi) { unsigned r; asm volatile("v_cvt_pk_bf16_f32 %0, %1, %2" : "=v"(r) : "v"(lo), "v"(hi)); return r; }
; __device__ __forceinline__ float rs_of(const float* ss, int row) { return 1.0f / sqrtf(ss[row] * (1.0f / 2048.0f) + 1e-5f); }
; __device__ __forceinline__ u32x4 pack8(f32x4 a, f32x4 b) { u32x4 w; w.x = cvt_pk_bf16(a[0], a[1]); w.y = cvt_pk_bf16(a[2], a[3]); w.z = cvt_pk_bf16(b[0], b[1]); w.w = cvt_pk_bf16(b[2], b[3]); return w; }
; __device__ __forceinline__ void line_xchg(u32x4& v0, u32x4& v1, bool hb) {
;     u32x4 send = hb ? v0 : v1, recv;
;     recv.x = (unsigned)__builtin_amdgcn_mov_dpp((int)send.x, 0x128, 0xF, 0xF, false); recv.y = (unsigned)__builtin_amdgcn_mov_dpp((int)send.y, 0x128, 0xF, 0xF, false);
;     recv.z = (unsigned)__builtin_amdgcn_mov_dpp((int)send.z, 0x128, 0xF, 0xF, false); recv.w = (unsigned)__builtin_amdgcn_mov_dpp((int)send.w, 0x128, 0xF, 0xF, false);
;     const u32x4 o0 = hb ? recv : v0, o1 = hb ? v1 : recv; v0 = o0; v1 = o1;
; }
;     __device__ __forceinline__ void operator()(const f32x4 (&acc)[2][2][4][2], const Unit& u, int wr, int wc, int fr, int fq) const {
;     ...
; #pragma unroll
;         for (int ai = 0; ai < 2; ++ai)
; #pragma unroll
;             for (int m = 0; m < 4; ++m) {
;                 const int row = row0 + ai * HALF + m * 16; const float rr = ss ? rs_of(ss, row) : 1.0f;
;                 u32x4 v[2];
; #pragma unroll
;                 for (int bj = 0; bj < 2; ++bj) {
;                     f32x4 a = __builtin_elementwise_max(acc[ai][bj][m][0], z) * rr, b = __builtin_elementwise_max(acc[ai][bj][m][1], z) * rr;
;                     v[bj] = pack8(a * a, b * b);
;                 }
;                 line_xchg(v[0], v[1], hb);
;                 bf16_t* p = O + (size_t)(srow0 + ai * HALF + m * 16) * ldc + scol;
;                 __builtin_nontemporal_store(v[0], (u32x4*)p); __builtin_nontemporal_store(v[1], (u32x4*)(p + (size_t)8 * ldc));
;             }
	v_pk_mul_f32 v[66:67], v[66:67], v[80:81] op_sel_hi:[1,0]
	v_pk_mul_f32 v[64:65], v[64:65], v[64:65]
	v_cvt_pk_bf16_f32 v76, v76, v77
	v_cvt_pk_bf16_f32 v77, v78, v79
	v_cvt_pk_bf16_f32 v72, v72, v73
	v_cvt_pk_bf16_f32 v73, v74, v75
	v_pk_mul_f32 v[70:71], v[70:71], v[70:71]
	v_pk_mul_f32 v[68:69], v[68:69], v[68:69]
	v_pk_mul_f32 v[66:67], v[66:67], v[66:67]
	v_cvt_pk_bf16_f32 v74, v68, v69
	v_cvt_pk_bf16_f32 v75, v70, v71
	v_cvt_pk_bf16_f32 v78, v64, v65
	s_nop 0
	v_cndmask_b32_e64 v65, v78, v72, s[2:3]
	v_cvt_pk_bf16_f32 v67, v66, v67
	v_cndmask_b32_e64 v66, v75, v77, s[2:3]
	v_cndmask_b32_e64 v64, v67, v73, s[2:3]
	v_mov_b32_dpp v80, v65 row_ror:8 row_mask:0xf bank_mask:0xf
	v_cndmask_b32_e64 v70, v72, v80, s[2:3]
	v_mov_b32_dpp v81, v64 row_ror:8 row_mask:0xf bank_mask:0xf
	v_or_b32_e32 v72, 48, v136
	v_cndmask_b32_e64 v71, v73, v81, s[2:3]
	v_ashrrev_i32_e32 v73, 31, v72
	v_cndmask_b32_e64 v68, v74, v76, s[2:3]
	v_lshlrev_b64 v[72:73], 14, v[72:73]
	v_mov_b32_dpp v66, v66 row_ror:8 row_mask:0xf bank_mask:0xf
	v_mov_b32_dpp v79, v68 row_ror:8 row_mask:0xf bank_mask:0xf
	v_lshl_add_u64 v[72:73], s[10:11], 0, v[72:73]
	v_cndmask_b32_e64 v68, v76, v79, s[2:3]
	v_cndmask_b32_e64 v69, v77, v66, s[2:3]
	v_lshl_add_u64 v[72:73], v[72:73], 0, v[122:123]
	global_store_dwordx4 v[72:73], v[68:71], off nt
	v_cndmask_b32_e64 v64, v79, v74, s[2:3]
	v_cndmask_b32_e64 v65, v66, v75, s[2:3]
	v_add_co_u32_e32 v68, vcc, s79, v72
	v_cndmask_b32_e64 v66, v80, v78, s[2:3]
	v_cndmask_b32_e64 v67, v81, v67, s[2:3]
	v_addc_co_u32_e32 v69, vcc, 0, v73, vcc
	global_store_dwordx4 v[68:69], v[64:67], off nt
	s_nop 1
	s_mov_b32 s0, 0x200000
	v_mov_b32_e32 v64, v238
	v_pk_mul_f32 v[60:61], v[60:61], v[64:65] op_sel_hi:[1,0]
	v_pk_mul_f32 v[62:63], v[62:63], v[64:65] op_sel_hi:[1,0]
	v_pk_mul_f32 v[56:57], v[56:57], v[64:65] op_sel_hi:[1,0]
	v_pk_mul_f32 v[58:59], v[58:59], v[64:65] op_sel_hi:[1,0]
	v_pk_mul_f32 v[48:49], v[48:49], v[64:65] op_sel_hi:[1,0]
	v_pk_mul_f32 v[62:63], v[62:63], v[62:63]
	v_pk_mul_f32 v[60:61], v[60:61], v[60:61]
	v_pk_mul_f32 v[58:59], v[58:59], v[58:59]
	v_pk_mul_f32 v[56:57], v[56:57], v[56:57]
	v_pk_mul_f32 v[52:53], v[52:53], v[64:65] op_sel_hi:[1,0]
	v_pk_mul_f32 v[54:55], v[54:55], v[64:65] op_sel_hi:[1,0]
	v_pk_mul_f32 v[50:51], v[50:51], v[64:65] op_sel_hi:[1,0]
	v_pk_mul_f32 v[48:49], v[48:49], v[48:49]
	v_cvt_pk_bf16_f32 v60, v60, v61
	v_cvt_pk_bf16_f32 v61, v62, v63
	v_cvt_pk_bf16_f32 v56, v56, v57
	v_cvt_pk_bf16_f32 v57, v58, v59
	v_pk_mul_f32 v[54:55], v[54:55], v[54:55]
	v_pk_mul_f32 v[52:53], v[52:53], v[52:53]
	v_pk_mul_f32 v[50:51], v[50:51], v[50:51]
	v_cvt_pk_bf16_f32 v58, v52, v53
	v_cvt_pk_bf16_f32 v59, v54, v55
	v_cvt_pk_bf16_f32 v62, v48, v49
	s_nop 0
	v_cndmask_b32_e64 v49, v62, v56, s[2:3]
	v_cvt_pk_bf16_f32 v51, v50, v51
	v_cndmask_b32_e64 v50, v59, v61, s[2:3]
	v_cndmask_b32_e64 v48, v51, v57, s[2:3]
	v_cndmask_b32_e64 v52, v58, v60, s[2:3]
	v_mov_b32_dpp v64, v49 row_ror:8 row_mask:0xf bank_mask:0xf
	v_mov_b32_dpp v50, v50 row_ror:8 row_mask:0xf bank_mask:0xf
	v_mov_b32_dpp v63, v52 row_ror:8 row_mask:0xf bank_mask:0xf
	v_mov_b32_dpp v65, v48 row_ror:8 row_mask:0xf bank_mask:0xf
	v_cndmask_b32_e64 v54, v56, v64, s[2:3]
	v_add_co_u32_e32 v56, vcc, s0, v120
	v_cndmask_b32_e64 v52, v60, v63, s[2:3]
	v_cndmask_b32_e64 v53, v61, v50, s[2:3]
	v_cndmask_b32_e64 v55, v57, v65, s[2:3]
	v_addc_co_u32_e32 v57, vcc, 0, v121, vcc
	s_mov_b32 s0, 0x220000
	global_store_dwordx4 v[56:57], v[52:55], off nt
	v_cndmask_b32_e64 v48, v63, v58, s[2:3]
	v_cndmask_b32_e64 v49, v50, v59, s[2:3]
	v_add_co_u32_e32 v52, vcc, s0, v120
	v_cndmask_b32_e64 v50, v64, v62, s[2:3]
	v_cndmask_b32_e64 v51, v65, v51, s[2:3]
	v_addc_co_u32_e32 v53, vcc, 0, v121, vcc
	global_store_dwordx4 v[52:53], v[48:51], off nt
	s_nop 1
	s_mov_b32 s0, 0x240000
	v_mov_b32_e32 v48, v239
	v_pk_mul_f32 v[44:45], v[44:45], v[48:49] op_sel_hi:[1,0]
	v_pk_mul_f32 v[40:41], v[40:41], v[48:49] op_sel_hi:[1,0]
	v_pk_mul_f32 v[36:37], v[36:37], v[48:49] op_sel_hi:[1,0]
	v_pk_mul_f32 v[38:39], v[38:39], v[48:49] op_sel_hi:[1,0]
	v_pk_mul_f32 v[32:33], v[32:33], v[48:49] op_sel_hi:[1,0]
	v_pk_mul_f32 v[46:47], v[46:47], v[48:49] op_sel_hi:[1,0]
	v_pk_mul_f32 v[42:43], v[42:43], v[48:49] op_sel_hi:[1,0]
	v_pk_mul_f32 v[44:45], v[44:45], v[44:45]
	v_pk_mul_f32 v[40:41], v[40:41], v[40:41]
	v_pk_mul_f32 v[34:35], v[34:35], v[48:49] op_sel_hi:[1,0]
	v_pk_mul_f32 v[38:39], v[38:39], v[38:39]
	v_pk_mul_f32 v[36:37], v[36:37], v[36:37]
	v_pk_mul_f32 v[32:33], v[32:33], v[32:33]
	v_pk_mul_f32 v[46:47], v[46:47], v[46:47]
	v_pk_mul_f32 v[42:43], v[42:43], v[42:43]
	v_cvt_pk_bf16_f32 v44, v44, v45
	v_cvt_pk_bf16_f32 v45, v46, v47
	v_cvt_pk_bf16_f32 v40, v40, v41
	v_pk_mul_f32 v[34:35], v[34:35], v[34:35]
	v_cvt_pk_bf16_f32 v41, v42, v43
	v_cvt_pk_bf16_f32 v36, v36, v37
	v_cvt_pk_bf16_f32 v37, v38, v39
	v_cvt_pk_bf16_f32 v38, v32, v33
	s_nop 0
	v_cndmask_b32_e64 v33, v38, v40, s[2:3]
	v_cvt_pk_bf16_f32 v39, v34, v35
	v_cndmask_b32_e64 v34, v37, v45, s[2:3]
	v_cndmask_b32_e64 v32, v39, v41, s[2:3]
	v_cndmask_b32_e64 v35, v36, v44, s[2:3]
	v_mov_b32_dpp v46, v33 row_ror:8 row_mask:0xf bank_mask:0xf
; template <class Epi, class Sched, bool ALIGN_EPI = false, bool SP2 = false>
; __device__ __forceinline__ void gemm_phase(PG8_LAS unsigned char* lds, const Gemm g, const Sched& S, const Epi& E) {
;     ...
;         if constexpr (ALIGN_EPI) { if (wr == 0) PG8_BAR; }
;         if constexpr (!Epi::AFTER_DRAIN) { E(acc, cur, wr, wc, fr, fq); S.done(cur); }
;         if (!has_next) break;
; #pragma unroll
;         for (int a = 0; a < 2; ++a)
; #pragma unroll
;             for (int b = 0; b < 2; ++b)
; #pragma unroll
;                 for (int m = 0; m < 4; ++m)
; #pragma unroll
;                     for (int n = 0; n < 2; ++n) acc[a][b][m][n] = (f32x4){0.f, 0.f, 0.f, 0.f};
; __device__ __forceinline__ u32x4 pack8(f32x4 a, f32x4 b) { u32x4 w; w.x = cvt_pk_bf16(a[0], a[1]); w.y = cvt_pk_bf16(a[2], a[3]); w.z = cvt_pk_bf16(b[0], b[1]); w.w = cvt_pk_bf16(b[2], b[3]); return w; }
; __device__ __forceinline__ void line_xchg(u32x4& v0, u32x4& v1, bool hb) {
;     u32x4 send = hb ? v0 : v1, recv;
;     recv.x = (unsigned)__builtin_amdgcn_mov_dpp((int)send.x, 0x128, 0xF, 0xF, false); recv.y = (unsigned)__builtin_amdgcn_mov_dpp((int)send.y, 0x128, 0xF, 0xF, false);
;     recv.z = (unsigned)__builtin_amdgcn_mov_dpp((int)send.z, 0x128, 0xF, 0xF, false); recv.w = (unsigned)__builtin_amdgcn_mov_dpp((int)send.w, 0x128, 0xF, 0xF, false);
;     const u32x4 o0 = hb ? recv : v0, o1 = hb ? v1 : recv; v0 = o0; v1 = o1;
; }
;     __device__ __forceinline__ void operator()(const f32x4 (&acc)[2][2][4][2], const Unit& u, int wr, int wc, int fr, int fq) const {
;     ...
; #pragma unroll
;         for (int ai = 0; ai < 2; ++ai)
; #pragma unroll
;             for (int m = 0; m < 4; ++m) {
;                 const int row = row0 + ai * HALF + m * 16; const float rr = ss ? rs_of(ss, row) : 1.0f;
;                 u32x4 v[2];
; #pragma unroll
;                 for (int bj = 0; bj < 2; ++bj) {
;                     f32x4 a = __builtin_elementwise_max(acc[ai][bj][m][0], z) * rr, b = __builtin_elementwise_max(acc[ai][bj][m][1], z) * rr;
;                     v[bj] = pack8(a * a, b * b);
;                 }
;                 line_xchg(v[0], v[1], hb);
;                 bf16_t* p = O + (size_t)(srow0 + ai * HALF + m * 16) * ldc + scol;
;                 __builtin_nontemporal_store(v[0], (u32x4*)p); __builtin_nontemporal_store(v[1], (u32x4*)(p + (size_t)8 * ldc));
;             }
	v_mov_b32_dpp v43, v34 row_ror:8 row_mask:0xf bank_mask:0xf
	v_mov_b32_dpp v42, v35 row_ror:8 row_mask:0xf bank_mask:0xf
	v_mov_b32_dpp v47, v32 row_ror:8 row_mask:0xf bank_mask:0xf
	v_cndmask_b32_e64 v34, v40, v46, s[2:3]
	v_add_co_u32_e32 v40, vcc, s0, v120
	v_cndmask_b32_e64 v32, v44, v42, s[2:3]
	v_cndmask_b32_e64 v33, v45, v43, s[2:3]
	v_cndmask_b32_e64 v35, v41, v47, s[2:3]
	v_addc_co_u32_e32 v41, vcc, 0, v121, vcc
	s_mov_b32 s0, 0x260000
	global_store_dwordx4 v[40:41], v[32:35], off nt
	v_cndmask_b32_e64 v36, v42, v36, s[2:3]
	v_cndmask_b32_e64 v37, v43, v37, s[2:3]
	v_add_co_u32_e32 v32, vcc, s0, v120
	v_cndmask_b32_e64 v38, v46, v38, s[2:3]
	v_cndmask_b32_e64 v39, v47, v39, s[2:3]
	v_addc_co_u32_e32 v33, vcc, 0, v121, vcc
	global_store_dwordx4 v[32:33], v[36:39], off nt
	s_nop 1
	s_mov_b32 s0, 0x280000
	v_mov_b32_e32 v32, v240
	v_pk_mul_f32 v[28:29], v[28:29], v[32:33] op_sel_hi:[1,0]
	v_pk_mul_f32 v[24:25], v[24:25], v[32:33] op_sel_hi:[1,0]
	v_pk_mul_f32 v[20:21], v[20:21], v[32:33] op_sel_hi:[1,0]
	v_pk_mul_f32 v[22:23], v[22:23], v[32:33] op_sel_hi:[1,0]
	v_pk_mul_f32 v[16:17], v[16:17], v[32:33] op_sel_hi:[1,0]
	v_pk_mul_f32 v[30:31], v[30:31], v[32:33] op_sel_hi:[1,0]
	v_pk_mul_f32 v[26:27], v[26:27], v[32:33] op_sel_hi:[1,0]
	v_pk_mul_f32 v[28:29], v[28:29], v[28:29]
	v_pk_mul_f32 v[24:25], v[24:25], v[24:25]
	v_pk_mul_f32 v[18:19], v[18:19], v[32:33] op_sel_hi:[1,0]
	v_pk_mul_f32 v[22:23], v[22:23], v[22:23]
	v_pk_mul_f32 v[20:21], v[20:21], v[20:21]
	v_pk_mul_f32 v[16:17], v[16:17], v[16:17]
	v_pk_mul_f32 v[30:31], v[30:31], v[30:31]
	v_pk_mul_f32 v[26:27], v[26:27], v[26:27]
	v_cvt_pk_bf16_f32 v28, v28, v29
	v_cvt_pk_bf16_f32 v29, v30, v31
	v_cvt_pk_bf16_f32 v24, v24, v25
	v_pk_mul_f32 v[18:19], v[18:19], v[18:19]
	v_cvt_pk_bf16_f32 v25, v26, v27
	v_cvt_pk_bf16_f32 v20, v20, v21
	v_cvt_pk_bf16_f32 v21, v22, v23
	v_cvt_pk_bf16_f32 v22, v16, v17
	s_nop 0
	v_cndmask_b32_e64 v17, v22, v24, s[2:3]
	v_cvt_pk_bf16_f32 v23, v18, v19
	v_cndmask_b32_e64 v18, v21, v29, s[2:3]
	v_cndmask_b32_e64 v16, v23, v25, s[2:3]
	v_cndmask_b32_e64 v19, v20, v28, s[2:3]
	v_mov_b32_dpp v30, v17 row_ror:8 row_mask:0xf bank_mask:0xf
	v_mov_b32_dpp v27, v18 row_ror:8 row_mask:0xf bank_mask:0xf
	v_mov_b32_dpp v26, v19 row_ror:8 row_mask:0xf bank_mask:0xf
	v_mov_b32_dpp v31, v16 row_ror:8 row_mask:0xf bank_mask:0xf
	v_cndmask_b32_e64 v18, v24, v30, s[2:3]
	v_add_co_u32_e32 v24, vcc, s0, v120
	v_cndmask_b32_e64 v16, v28, v26, s[2:3]
	v_cndmask_b32_e64 v17, v29, v27, s[2:3]
	v_cndmask_b32_e64 v19, v25, v31, s[2:3]
	v_addc_co_u32_e32 v25, vcc, 0, v121, vcc
	s_mov_b32 s0, 0x2a0000
	global_store_dwordx4 v[24:25], v[16:19], off nt
	v_cndmask_b32_e64 v20, v26, v20, s[2:3]
	v_cndmask_b32_e64 v21, v27, v21, s[2:3]
	v_add_co_u32_e32 v16, vcc, s0, v120
	v_cndmask_b32_e64 v22, v30, v22, s[2:3]
	v_cndmask_b32_e64 v23, v31, v23, s[2:3]
	v_addc_co_u32_e32 v17, vcc, 0, v121, vcc
	global_store_dwordx4 v[16:17], v[20:23], off nt
	s_nop 1
	s_mov_b64 s[0:1], -1
	v_mov_b32_e32 v16, v241
	v_pk_mul_f32 v[12:13], v[12:13], v[16:17] op_sel_hi:[1,0]
	v_pk_mul_f32 v[14:15], v[14:15], v[16:17] op_sel_hi:[1,0]
	v_pk_mul_f32 v[8:9], v[8:9], v[16:17] op_sel_hi:[1,0]
	v_pk_mul_f32 v[10:11], v[10:11], v[16:17] op_sel_hi:[1,0]
	v_pk_mul_f32 v[0:1], v[0:1], v[16:17] op_sel_hi:[1,0]
	v_pk_mul_f32 v[14:15], v[14:15], v[14:15]
	v_pk_mul_f32 v[12:13], v[12:13], v[12:13]
	v_pk_mul_f32 v[10:11], v[10:11], v[10:11]
	v_pk_mul_f32 v[8:9], v[8:9], v[8:9]
	v_pk_mul_f32 v[4:5], v[4:5], v[16:17] op_sel_hi:[1,0]
	v_pk_mul_f32 v[6:7], v[6:7], v[16:17] op_sel_hi:[1,0]
	v_pk_mul_f32 v[2:3], v[2:3], v[16:17] op_sel_hi:[1,0]
	v_pk_mul_f32 v[0:1], v[0:1], v[0:1]
	v_cvt_pk_bf16_f32 v12, v12, v13
	v_cvt_pk_bf16_f32 v13, v14, v15
	v_cvt_pk_bf16_f32 v8, v8, v9
	v_cvt_pk_bf16_f32 v9, v10, v11
	v_pk_mul_f32 v[6:7], v[6:7], v[6:7]
	v_pk_mul_f32 v[4:5], v[4:5], v[4:5]
	v_pk_mul_f32 v[2:3], v[2:3], v[2:3]
	v_cvt_pk_bf16_f32 v10, v4, v5
	v_cvt_pk_bf16_f32 v11, v6, v7
	v_cvt_pk_bf16_f32 v14, v0, v1
	s_nop 0
	v_cndmask_b32_e64 v1, v14, v8, s[2:3]
	v_cvt_pk_bf16_f32 v3, v2, v3
	v_cndmask_b32_e64 v2, v11, v13, s[2:3]
	v_cndmask_b32_e64 v0, v3, v9, s[2:3]
	v_cndmask_b32_e64 v4, v10, v12, s[2:3]
	v_mov_b32_dpp v16, v1 row_ror:8 row_mask:0xf bank_mask:0xf
	v_mov_b32_dpp v2, v2 row_ror:8 row_mask:0xf bank_mask:0xf
	v_mov_b32_dpp v15, v4 row_ror:8 row_mask:0xf bank_mask:0xf
	v_mov_b32_dpp v17, v0 row_ror:8 row_mask:0xf bank_mask:0xf
	v_cndmask_b32_e64 v6, v8, v16, s[2:3]
	v_add_co_u32_e32 v8, vcc, 0x2c0000, v120
	v_cndmask_b32_e64 v4, v12, v15, s[2:3]
	v_cndmask_b32_e64 v5, v13, v2, s[2:3]
	v_cndmask_b32_e64 v7, v9, v17, s[2:3]
	v_addc_co_u32_e32 v9, vcc, 0, v121, vcc
	global_store_dwordx4 v[8:9], v[4:7], off nt
	v_cndmask_b32_e64 v0, v15, v10, s[2:3]
	v_cndmask_b32_e64 v1, v2, v11, s[2:3]
	v_add_co_u32_e32 v4, vcc, 0x2e0000, v120
	v_cndmask_b32_e64 v2, v16, v14, s[2:3]
	s_nop 0
	v_addc_co_u32_e32 v5, vcc, 0, v121, vcc
	v_cndmask_b32_e64 v3, v17, v3, s[2:3]
	s_andn2_b64 vcc, exec, s[4:5]
	global_store_dwordx4 v[4:5], v[0:3], off nt
	s_cbranch_vccnz .LBB0_702
	s_andn2_b64 vcc, exec, s[8:9]
	s_cbranch_vccnz .LBB0_701
	s_barrier
	s_branch .LBB0_701
